# down GEMM tail: sample-row tiles split 4-way along K into f32 partial slabs, folded in a hand-written final rmsnorm phase
# speedup vs baseline: 1.0791x; 1.0531x over previous
; #define LAS __attribute__((address_space(3)))
; __device__ __forceinline__ int opaque_bid() { int t = blockIdx.x; asm volatile("" : "+s"(t)); return t; }
;     __device__ bool next(int i, Unit& u) const {
;         const long L = (long)i * G + c; if (L >= nwg) return false;
;         int wgid = (int)L; { const int q = nwg / NXCD, r = nwg % NXCD, xcd = wgid % NXCD, off = wgid / NXCD; wgid = (xcd < r ? xcd * (q + 1) : r * (q + 1) + (xcd - r) * q) + off; }
;         const int nig = WGM * nN, gid = wgid / nig, fm = gid * WGM, gsz = (nM - fm) < WGM ? (nM - fm) : WGM;
;         u.pm = fm + ((wgid % nig) % gsz); u.pn = (wgid % nig) / gsz; return true;
; __global__ void __launch_bounds__(512, 2) hymba_fwd(Params p0) {
;     ...
;         case 7: if (PH_MASK & 128) { pg8::Gemm g{(const bf16_t*)(p.ws + WS_ACT), (const bf16_t*)(p.ws + WS_WDOWN), MP, 2048, DFF}; pg8::StaticOrder S; S.init(MP, 2048, gridDim.x, opaque_bid());
;                   Epi4 E{(const float*)(p.ws + WS_H1), p.out, (float*)(p.ws + WS_SS3)}; pg8::gemm_phase((LAS unsigned char*)smem, g, S, E); } break;
.LBB0_5:
	v_readlane_b32 s0, v254, 26
	s_mov_b64 s[4:5], 0
	v_readlane_b32 s2, v254, 28
	v_readlane_b32 s3, v254, 29
	s_add_u32 s82, s2, s4
	s_addc_u32 s83, s3, s5
	v_writelane_b32 v255, s4, 27
	s_lshl_b64 s[2:3], s[4:5], 2
	v_readlane_b32 s1, v254, 27
	v_writelane_b32 v255, s5, 28
	s_add_u32 s0, s0, s2
	v_writelane_b32 v255, s2, 29
	s_addc_u32 s1, s1, s3
	s_mov_b64 s[10:11], 0
	v_writelane_b32 v255, s3, 30
	v_readlane_b32 s2, v254, 1
	v_writelane_b32 v255, s0, 31
	v_readlane_b32 s3, v254, 2
	s_cmp_lt_i32 s2, 4
	v_writelane_b32 v255, s1, 32
	s_mov_b64 s[2:3], 0
	v_writelane_b32 v255, s2, 33
	s_mov_b64 s[0:1], -1
	s_nop 0
	v_writelane_b32 v255, s3, 34
	s_cbranch_scc1 .LBB0_416
	v_readlane_b32 s0, v254, 1
	s_cmp_gt_i32 s0, 5
	v_readlane_b32 s1, v254, 2
	s_cbranch_scc0 .LBB0_48
	s_cmp_gt_i32 s0, 6
	s_cbranch_scc0 .LBB0_49
	s_cmp_eq_u32 s0, 7
	s_mov_b64 s[0:1], -1
	s_cbranch_scc0 .LBB0_54
	v_readlane_b32 s22, v254, 0
	s_waitcnt vmcnt(0)
	v_mov_b32_e32 v12, v151
	s_cmpk_lt_i32 s22, 0x128
	s_cselect_b64 s[0:1], -1, 0
	s_cmpk_gt_i32 s22, 0x127
	v_readfirstlane_b32 s23, v12
	s_cbranch_scc1 .LBB0_11
	s_ashr_i32 s2, s22, 31
	s_lshr_b32 s2, s2, 29
	s_add_i32 s2, s22, s2
	s_ashr_i32 s3, s2, 3
	s_and_b32 s2, s2, -8
	s_sub_i32 s2, s22, s2
	s_cmp_lt_i32 s2, 0
	s_cselect_b32 s4, 33, 32
	s_mul_i32 s2, s2, s4
	s_add_i32 s2, s2, s3
	s_ashr_i32 s3, s2, 31
	s_lshr_b32 s3, s3, 26
	s_add_i32 s3, s2, s3
	s_ashr_i32 s4, s3, 6
	s_lshl_b32 s4, s4, 3
	s_sub_i32 s5, 37, s4
	s_min_u32 s5, s5, 8
	s_andn2_b32 s3, s3, 63
	s_sub_i32 s6, s2, s3
	s_waitcnt lgkmcnt(0)
	v_cvt_f32_ubyte0_e32 v5, s5
	v_cvt_f32_i32_e32 v4, s6
	v_rcp_iflag_f32_e32 v6, v5
	s_ashr_i32 s2, s6, 30
	s_or_b32 s7, s2, 1
	v_mul_f32_e32 v6, v4, v6
	v_trunc_f32_e32 v6, v6
	v_fma_f32 v4, -v6, v5, v4
	v_cvt_i32_f32_e32 v6, v6
	v_cmp_ge_f32_e64 s[2:3], |v4|, v5
	s_and_b64 s[2:3], s[2:3], exec
	s_cselect_b32 s2, s7, 0
	v_readfirstlane_b32 s3, v6
	s_add_i32 s2, s3, s2
	s_sext_i32_i8 s28, s2
	s_mul_i32 s2, s2, s5
	s_sub_i32 s2, s6, s2
	s_sext_i32_i8 s2, s2
	s_add_i32 s29, s4, s2

; #define PG8_STAGE(bufoff, gbase, voff) do { _Pragma("unroll") for (int _i = 0; _i < 2; ++_i) \
;         __builtin_amdgcn_global_load_lds((const unsigned*)((const char*)(gbase) + (voff)[_i]), (LAS unsigned*)(lds + (bufoff) + ldsw + _i * 8192), 16, 0, 0); } while (0)
; #define PG8_LDA(dst, b, h) do { _Pragma("unroll") for (int m = 0; m < 4; ++m) _Pragma("unroll") for (int k = 0; k < 2; ++k) dst[m][k] = *(const LAS bf16x8*)(lds + PG8_SA(b, h) + aoff + m * 2048 + k * 1024); } while (0)
; #define PG8_LDB(dst, b, h) do { _Pragma("unroll") for (int n = 0; n < 2; ++n) _Pragma("unroll") for (int k = 0; k < 2; ++k) dst[n][k] = *(const LAS bf16x8*)(lds + PG8_SB(b, h) + boff + n * 2048 + k * 1024); } while (0)
; #define PG8_MMA(ai, bj, At, Bt) do { __builtin_amdgcn_s_setprio(1); _Pragma("unroll") for (int m = 0; m < 4; ++m) _Pragma("unroll") for (int n = 0; n < 2; ++n) _Pragma("unroll") for (int k = 0; k < 2; ++k) \
;         acc[ai][bj][m][n] = __builtin_amdgcn_mfma_f32_16x16x32_bf16(Bt[n][k], At[m][k], acc[ai][bj][m][n], 0, 0, 0); __builtin_amdgcn_s_setprio(0); } while (0)
; #define PG8_BAR __builtin_amdgcn_s_barrier()
; template <class Epi>
; __device__ __forceinline__ void gemm_phase(LAS unsigned char* lds, const Gemm g, const StaticOrder& S, const Epi& E) {
;     ...
;         const bool has_next = S.next(ui + 1, nxt);
;         const char* nA = has_next ? (const char*)g.A + (size_t)nxt.pm * tstep : cA; const char* nB = has_next ? (const char*)g.Bt + (size_t)nxt.pn * tstep : cB;
;         for (int t = 0; t < nt; t += 2) {
;             const bool last = (t == nt - 2);
;             const char* a1 = cA + (size_t)(t + 1) * kstep;
;             const char* a2 = last ? nA : cA + (size_t)(t + 2) * kstep; const char* b2 = last ? nB : cB + (size_t)(t + 2) * kstep;
;             const char* a3 = a2 + kstep; const char* b3 = b2 + kstep;
;             PG8_LDB(B0, 0, 0); PG8_SCHED; PG8_LDA(At, 0, 0); PG8_STAGE(PG8_SA(1, 1), a1 + hstep, voffA);
;             PG8_WAIT_L(8); PG8_BAR; PG8_WAIT_L(0); PG8_MMA(0, 0, At, B0); PG8_BAR; PG8_SCHED;
;     ...
; #pragma unroll
;         for (int a = 0; a < 2; ++a)
; #pragma unroll
;             for (int b = 0; b < 2; ++b)
; #pragma unroll
;                 for (int m = 0; m < 4; ++m)
; #pragma unroll
;                     for (int n = 0; n < 2; ++n) acc[a][b][m][n] = (f32x4){0.f, 0.f, 0.f, 0.f};
;         cur = nxt; cA = nA; cB = nB; ++ui;
.LBB0_16:
	s_mov_b64 s[18:19], s[0:1]
	s_add_i32 s40, s40, 1
	s_mov_b64 s[16:17], s[14:15]
	s_mov_b32 s42, s28
	s_mov_b32 s43, s29
	s_cmp_eq_u32 s40, 1
	s_cselect_b32 s6, 1, 0
	s_cmpk_lt_u32 s22, 0x80
	s_cselect_b32 s7, 1, 0
	s_and_b32 s6, s6, s7
	s_cmp_lg_u32 s6, 0
	s_cselect_b64 s[4:5], 0, -1
	s_mov_b64 s[14:15], s[16:17]
	s_mov_b64 s[0:1], s[18:19]
	s_cbranch_scc0 .Lp7_units_done
	s_lshr_b32 s6, s22, 2
	s_and_b32 s28, s6, 7
	s_lshr_b32 s29, s6, 3
	s_add_i32 s29, s29, 32
	s_and_b32 s6, s22, 3
	s_mul_i32 s6, s6, 0xb00
	s_mul_i32 s7, s29, 0x2c0000
	s_add_u32 s7, s7, s6
	s_add_u32 s14, s24, s7
	s_addc_u32 s15, s25, 0
	s_mul_i32 s7, s28, 0x2c0000
	s_add_u32 s7, s7, s6
	s_add_u32 s0, s26, s7
	s_addc_u32 s1, s27, 0
.Lp7_units_done:
	s_add_u32 s44, s18, 0x100
	v_mov_b32_e32 v4, 0
	s_addc_u32 s46, s19, 0
	s_cmp_eq_u32 s40, 1
	s_cselect_b32 s47, -2, 64
	s_waitcnt lgkmcnt(0)
	v_mov_b32_e32 v5, v4
	v_mov_b32_e32 v6, v4
	v_mov_b32_e32 v7, v4
	v_mov_b32_e32 v8, v4
	v_mov_b32_e32 v9, v4
	v_mov_b32_e32 v10, v4
	v_mov_b32_e32 v11, v4
	v_mov_b32_e32 v20, v4
	v_mov_b32_e32 v21, v4
	v_mov_b32_e32 v22, v4
	v_mov_b32_e32 v23, v4
	v_mov_b32_e32 v24, v4
	v_mov_b32_e32 v25, v4
	v_mov_b32_e32 v26, v4
	v_mov_b32_e32 v27, v4
	v_mov_b32_e32 v36, v4
	v_mov_b32_e32 v37, v4
	v_mov_b32_e32 v38, v4
	v_mov_b32_e32 v39, v4
	v_mov_b32_e32 v40, v4
	v_mov_b32_e32 v41, v4
	v_mov_b32_e32 v42, v4
	v_mov_b32_e32 v43, v4
	v_mov_b32_e32 v52, v4
	v_mov_b32_e32 v53, v4
	v_mov_b32_e32 v54, v4
	v_mov_b32_e32 v55, v4
	v_mov_b32_e32 v56, v4
	v_mov_b32_e32 v57, v4
	v_mov_b32_e32 v58, v4
	v_mov_b32_e32 v59, v4
	v_mov_b32_e32 v12, v4
	v_mov_b32_e32 v13, v4
	v_mov_b32_e32 v14, v4
	v_mov_b32_e32 v15, v4
	v_mov_b32_e32 v16, v4
	v_mov_b32_e32 v17, v4
	v_mov_b32_e32 v18, v4
	v_mov_b32_e32 v19, v4
	v_mov_b32_e32 v28, v4
	v_mov_b32_e32 v29, v4
	v_mov_b32_e32 v30, v4
	v_mov_b32_e32 v31, v4
	v_mov_b32_e32 v32, v4
	v_mov_b32_e32 v33, v4
	v_mov_b32_e32 v34, v4
	v_mov_b32_e32 v35, v4
	v_mov_b32_e32 v44, v4
	v_mov_b32_e32 v45, v4
	v_mov_b32_e32 v46, v4
	v_mov_b32_e32 v47, v4
	v_mov_b32_e32 v48, v4
	v_mov_b32_e32 v49, v4
	v_mov_b32_e32 v50, v4
	v_mov_b32_e32 v51, v4
	v_mov_b32_e32 v60, v4
	v_mov_b32_e32 v61, v4
	v_mov_b32_e32 v62, v4
	v_mov_b32_e32 v63, v4
	v_mov_b32_e32 v64, v4
	v_mov_b32_e32 v65, v4
	v_mov_b32_e32 v66, v4
	v_mov_b32_e32 v67, v4
	v_mov_b32_e32 v68, v4
	v_mov_b32_e32 v69, v4
	v_mov_b32_e32 v70, v4
	v_mov_b32_e32 v71, v4
	v_mov_b32_e32 v72, v4
	v_mov_b32_e32 v73, v4
	v_mov_b32_e32 v74, v4
	v_mov_b32_e32 v75, v4
	v_mov_b32_e32 v84, v4
	v_mov_b32_e32 v85, v4
	v_mov_b32_e32 v86, v4
	v_mov_b32_e32 v87, v4
	v_mov_b32_e32 v88, v4
	v_mov_b32_e32 v89, v4
	v_mov_b32_e32 v90, v4
	v_mov_b32_e32 v91, v4
	v_mov_b32_e32 v100, v4
	v_mov_b32_e32 v101, v4
	v_mov_b32_e32 v102, v4
	v_mov_b32_e32 v103, v4
	v_mov_b32_e32 v104, v4
	v_mov_b32_e32 v105, v4
	v_mov_b32_e32 v106, v4
	v_mov_b32_e32 v107, v4
	v_mov_b32_e32 v116, v4
	v_mov_b32_e32 v117, v4
	v_mov_b32_e32 v118, v4
	v_mov_b32_e32 v119, v4
	v_mov_b32_e32 v120, v4
	v_mov_b32_e32 v121, v4
	v_mov_b32_e32 v122, v4
	v_mov_b32_e32 v123, v4
	v_mov_b32_e32 v76, v4
	v_mov_b32_e32 v77, v4
	v_mov_b32_e32 v78, v4
	v_mov_b32_e32 v79, v4
	v_mov_b32_e32 v80, v4
	v_mov_b32_e32 v81, v4
	v_mov_b32_e32 v82, v4
	v_mov_b32_e32 v83, v4
	v_mov_b32_e32 v92, v4
	v_mov_b32_e32 v93, v4
	v_mov_b32_e32 v94, v4
	v_mov_b32_e32 v95, v4
	v_mov_b32_e32 v96, v4
	v_mov_b32_e32 v97, v4
	v_mov_b32_e32 v98, v4
	v_mov_b32_e32 v99, v4
	v_mov_b32_e32 v108, v4
	v_mov_b32_e32 v109, v4
	v_mov_b32_e32 v110, v4
	v_mov_b32_e32 v111, v4
	v_mov_b32_e32 v112, v4
	v_mov_b32_e32 v113, v4
	v_mov_b32_e32 v114, v4
	v_mov_b32_e32 v115, v4
	v_mov_b32_e32 v124, v4
	v_mov_b32_e32 v125, v4
	v_mov_b32_e32 v126, v4
	v_mov_b32_e32 v127, v4
	v_mov_b32_e32 v128, v4
	v_mov_b32_e32 v129, v4
	v_mov_b32_e32 v130, v4
	v_mov_b32_e32 v131, v4
.LBB0_23:
	s_add_u32 s6, s16, 0x100
	s_addc_u32 s7, s17, 0
	s_add_i32 s48, 0, 0x10000
	v_add_u32_e32 v178, s48, v147
	ds_read_b128 v[142:145], v178
	ds_read_b128 v[170:173], v178 offset:1024
	ds_read_b128 v[174:177], v178 offset:2048
	ds_read_b128 v[178:181], v178 offset:3072
	s_cmpk_eq_i32 s47, 0x54
	s_cselect_b32 s21, s15, s7
	s_cselect_b32 s20, s14, s6
	s_cselect_b32 s19, s1, s46
	s_cselect_b32 s18, s0, s44
	v_lshl_add_u64 v[226:227], s[16:17], 0, v[138:139]
	s_add_i32 m0, s31, 0xc000
	ds_read_b128 v[182:185], v163
	ds_read_b128 v[186:189], v163 offset:1024
	ds_read_b128 v[190:193], v163 offset:2048
	ds_read_b128 v[194:197], v163 offset:3072
	ds_read_b128 v[198:201], v163 offset:4096
	ds_read_b128 v[214:217], v163 offset:5120
	ds_read_b128 v[218:221], v163 offset:6144
	ds_read_b128 v[222:225], v163 offset:7168
	global_load_lds_dwordx4 v[226:227], off
	v_lshl_add_u64 v[226:227], s[16:17], 0, v[140:141]
	s_add_i32 m0, s31, 0xe000
	s_nop 0
	global_load_lds_dwordx4 v[226:227], off
	s_waitcnt lgkmcnt(8)
	s_barrier
	s_waitcnt lgkmcnt(0)
	s_setprio 1
	s_waitcnt lgkmcnt(0)
	v_mfma_f32_16x16x32_bf16 v[128:131], v[142:145], v[182:185], v[128:131]
	v_mfma_f32_16x16x32_bf16 v[124:127], v[174:177], v[182:185], v[124:127]
	v_mfma_f32_16x16x32_bf16 v[112:115], v[142:145], v[190:193], v[112:115]
	v_mfma_f32_16x16x32_bf16 v[108:111], v[174:177], v[190:193], v[108:111]
	v_mfma_f32_16x16x32_bf16 v[96:99], v[142:145], v[198:201], v[96:99]
	v_mfma_f32_16x16x32_bf16 v[92:95], v[174:177], v[198:201], v[92:95]
	v_mfma_f32_16x16x32_bf16 v[80:83], v[142:145], v[218:221], v[80:83]
	v_mfma_f32_16x16x32_bf16 v[76:79], v[174:177], v[218:221], v[76:79]
	v_mfma_f32_16x16x32_bf16 v[128:131], v[170:173], v[186:189], v[128:131]
	v_mfma_f32_16x16x32_bf16 v[124:127], v[178:181], v[186:189], v[124:127]
	v_mfma_f32_16x16x32_bf16 v[112:115], v[170:173], v[194:197], v[112:115]
	v_mfma_f32_16x16x32_bf16 v[108:111], v[178:181], v[194:197], v[108:111]
	v_mfma_f32_16x16x32_bf16 v[96:99], v[170:173], v[214:217], v[96:99]
	v_mfma_f32_16x16x32_bf16 v[92:95], v[178:181], v[214:217], v[92:95]
	v_mfma_f32_16x16x32_bf16 v[80:83], v[170:173], v[222:225], v[80:83]
	v_mfma_f32_16x16x32_bf16 v[76:79], v[178:181], v[222:225], v[76:79]
	s_setprio 0
	s_barrier
; #define PG8_STAGE(bufoff, gbase, voff) do { _Pragma("unroll") for (int _i = 0; _i < 2; ++_i) \
;         __builtin_amdgcn_global_load_lds((const unsigned*)((const char*)(gbase) + (voff)[_i]), (LAS unsigned*)(lds + (bufoff) + ldsw + _i * 8192), 16, 0, 0); } while (0)
; #define PG8_LDA(dst, b, h) do { _Pragma("unroll") for (int m = 0; m < 4; ++m) _Pragma("unroll") for (int k = 0; k < 2; ++k) dst[m][k] = *(const LAS bf16x8*)(lds + PG8_SA(b, h) + aoff + m * 2048 + k * 1024); } while (0)
; #define PG8_LDB(dst, b, h) do { _Pragma("unroll") for (int n = 0; n < 2; ++n) _Pragma("unroll") for (int k = 0; k < 2; ++k) dst[n][k] = *(const LAS bf16x8*)(lds + PG8_SB(b, h) + boff + n * 2048 + k * 1024); } while (0)
; #define PG8_MMA(ai, bj, At, Bt) do { __builtin_amdgcn_s_setprio(1); _Pragma("unroll") for (int m = 0; m < 4; ++m) _Pragma("unroll") for (int n = 0; n < 2; ++n) _Pragma("unroll") for (int k = 0; k < 2; ++k) \
;         acc[ai][bj][m][n] = __builtin_amdgcn_mfma_f32_16x16x32_bf16(Bt[n][k], At[m][k], acc[ai][bj][m][n], 0, 0, 0); __builtin_amdgcn_s_setprio(0); } while (0)
; #define PG8_WAIT_V(n) asm volatile("s_waitcnt vmcnt(" #n ")" ::: "memory")
; #define PG8_WAIT_L(n) asm volatile("s_waitcnt lgkmcnt(" #n ")" ::: "memory")
; #define PG8_BAR __builtin_amdgcn_s_barrier()
; #define PG8_SCHED __builtin_amdgcn_sched_barrier(0)
; template <class Epi>
; __device__ __forceinline__ void gemm_phase(LAS unsigned char* lds, const Gemm g, const StaticOrder& S, const Epi& E) {
;     ...
;             PG8_LDB(B1, 0, 1); PG8_STAGE(PG8_SB(0, 0), b2, voffB);
;             PG8_BAR; PG8_WAIT_L(0); PG8_MMA(0, 1, At, B1); PG8_BAR;
;             PG8_LDA(At, 0, 1); PG8_STAGE(PG8_SA(0, 0), a2, voffA);
;             PG8_BAR; PG8_WAIT_L(0); PG8_MMA(1, 0, At, B0); PG8_BAR; PG8_SCHED;
;             PG8_STAGE(PG8_SB(0, 1), b2 + hstep, voffB);
;             PG8_WAIT_V(6); PG8_BAR; PG8_MMA(1, 1, At, B1); PG8_BAR;
;             PG8_LDB(B0, 1, 0); PG8_SCHED; PG8_LDA(At, 1, 0); PG8_STAGE(PG8_SA(0, 1), a2 + hstep, voffA);
	s_add_i32 s52, 0, 0x14000
	s_add_i32 s16, s48, s30
	v_add_u32_e32 v238, s52, v147
	v_lshl_add_u64 v[242:243], s[18:19], 0, v[148:149]
	s_mov_b32 m0, s16
	ds_read_b128 v[226:229], v238
	ds_read_b128 v[230:233], v238 offset:1024
	ds_read_b128 v[234:237], v238 offset:2048
	ds_read_b128 v[238:241], v238 offset:3072
	global_load_lds_dwordx4 v[242:243], off
	v_lshl_add_u64 v[244:245], s[18:19], 0, v[136:137]
	s_add_i32 m0, s16, 0x2000
	s_nop 0
	global_load_lds_dwordx4 v[244:245], off
	s_barrier
	s_waitcnt lgkmcnt(0)
	s_setprio 1
	s_waitcnt lgkmcnt(0)
	v_mfma_f32_16x16x32_bf16 v[120:123], v[226:229], v[182:185], v[120:123]
	v_mfma_f32_16x16x32_bf16 v[116:119], v[234:237], v[182:185], v[116:119]
	v_mfma_f32_16x16x32_bf16 v[104:107], v[226:229], v[190:193], v[104:107]
	v_mfma_f32_16x16x32_bf16 v[100:103], v[234:237], v[190:193], v[100:103]
	v_mfma_f32_16x16x32_bf16 v[88:91], v[226:229], v[198:201], v[88:91]
	v_mfma_f32_16x16x32_bf16 v[84:87], v[234:237], v[198:201], v[84:87]
	v_mfma_f32_16x16x32_bf16 v[72:75], v[226:229], v[218:221], v[72:75]
	v_mfma_f32_16x16x32_bf16 v[68:71], v[234:237], v[218:221], v[68:71]
	v_mfma_f32_16x16x32_bf16 v[120:123], v[230:233], v[186:189], v[120:123]
	v_mfma_f32_16x16x32_bf16 v[116:119], v[238:241], v[186:189], v[116:119]
	v_mfma_f32_16x16x32_bf16 v[104:107], v[230:233], v[194:197], v[104:107]
	v_mfma_f32_16x16x32_bf16 v[100:103], v[238:241], v[194:197], v[100:103]
	v_mfma_f32_16x16x32_bf16 v[88:91], v[230:233], v[214:217], v[88:91]
	v_mfma_f32_16x16x32_bf16 v[84:87], v[238:241], v[214:217], v[84:87]
	v_mfma_f32_16x16x32_bf16 v[72:75], v[230:233], v[222:225], v[72:75]
	v_mfma_f32_16x16x32_bf16 v[68:71], v[238:241], v[222:225], v[68:71]
	s_setprio 0
	s_mov_b32 m0, s31
	v_lshl_add_u64 v[246:247], s[20:21], 0, v[132:133]
	s_barrier
	ds_read_b128 v[182:185], v163 offset:16384
	ds_read_b128 v[186:189], v163 offset:17408
	ds_read_b128 v[190:193], v163 offset:18432
	ds_read_b128 v[194:197], v163 offset:19456
	ds_read_b128 v[198:201], v163 offset:20480
	ds_read_b128 v[214:217], v163 offset:21504
	ds_read_b128 v[218:221], v163 offset:22528
	ds_read_b128 v[222:225], v163 offset:23552
	global_load_lds_dwordx4 v[246:247], off
	v_lshl_add_u64 v[248:249], s[20:21], 0, v[134:135]
	s_mov_b32 m0, s33
	s_nop 0
	global_load_lds_dwordx4 v[248:249], off
	s_barrier
	s_waitcnt lgkmcnt(0)
	s_setprio 1
	s_waitcnt lgkmcnt(0)
	v_mfma_f32_16x16x32_bf16 v[64:67], v[142:145], v[182:185], v[64:67]
	v_mfma_f32_16x16x32_bf16 v[60:63], v[174:177], v[182:185], v[60:63]
	v_mfma_f32_16x16x32_bf16 v[48:51], v[142:145], v[190:193], v[48:51]
	v_mfma_f32_16x16x32_bf16 v[44:47], v[174:177], v[190:193], v[44:47]
	v_mfma_f32_16x16x32_bf16 v[32:35], v[142:145], v[198:201], v[32:35]
	v_mfma_f32_16x16x32_bf16 v[28:31], v[174:177], v[198:201], v[28:31]
	v_mfma_f32_16x16x32_bf16 v[16:19], v[142:145], v[218:221], v[16:19]
	v_mfma_f32_16x16x32_bf16 v[12:15], v[174:177], v[218:221], v[12:15]
	v_mfma_f32_16x16x32_bf16 v[64:67], v[170:173], v[186:189], v[64:67]
	v_mfma_f32_16x16x32_bf16 v[60:63], v[178:181], v[186:189], v[60:63]
	v_mfma_f32_16x16x32_bf16 v[48:51], v[170:173], v[194:197], v[48:51]
	v_mfma_f32_16x16x32_bf16 v[44:47], v[178:181], v[194:197], v[44:47]
	v_mfma_f32_16x16x32_bf16 v[32:35], v[170:173], v[214:217], v[32:35]
	v_mfma_f32_16x16x32_bf16 v[28:31], v[178:181], v[214:217], v[28:31]
	v_mfma_f32_16x16x32_bf16 v[16:19], v[170:173], v[222:225], v[16:19]
	v_mfma_f32_16x16x32_bf16 v[12:15], v[178:181], v[222:225], v[12:15]
	s_setprio 0
	s_barrier
	s_add_u32 s16, s18, 0x160000
	s_addc_u32 s17, s19, 0
	s_add_i32 s48, s52, s30
	v_lshl_add_u64 v[142:143], s[16:17], 0, v[148:149]
	s_mov_b32 m0, s48
	s_nop 0
	global_load_lds_dwordx4 v[142:143], off
	v_lshl_add_u64 v[142:143], s[16:17], 0, v[136:137]
	s_add_i32 m0, s48, 0x2000
	s_nop 0
	global_load_lds_dwordx4 v[142:143], off
	s_waitcnt vmcnt(6)
	s_barrier
	s_setprio 1
	v_mfma_f32_16x16x32_bf16 v[56:59], v[226:229], v[182:185], v[56:59]
	v_mfma_f32_16x16x32_bf16 v[52:55], v[234:237], v[182:185], v[52:55]
	v_mfma_f32_16x16x32_bf16 v[40:43], v[226:229], v[190:193], v[40:43]
	v_mfma_f32_16x16x32_bf16 v[36:39], v[234:237], v[190:193], v[36:39]
	v_mfma_f32_16x16x32_bf16 v[24:27], v[226:229], v[198:201], v[24:27]
	v_mfma_f32_16x16x32_bf16 v[20:23], v[234:237], v[198:201], v[20:23]
	v_mfma_f32_16x16x32_bf16 v[8:11], v[226:229], v[218:221], v[8:11]
	v_mfma_f32_16x16x32_bf16 v[4:7], v[234:237], v[218:221], v[4:7]
	v_mfma_f32_16x16x32_bf16 v[56:59], v[230:233], v[186:189], v[56:59]
	v_mfma_f32_16x16x32_bf16 v[52:55], v[238:241], v[186:189], v[52:55]
	v_mfma_f32_16x16x32_bf16 v[40:43], v[230:233], v[194:197], v[40:43]
	v_mfma_f32_16x16x32_bf16 v[36:39], v[238:241], v[194:197], v[36:39]
	v_mfma_f32_16x16x32_bf16 v[24:27], v[230:233], v[214:217], v[24:27]
	v_mfma_f32_16x16x32_bf16 v[20:23], v[238:241], v[214:217], v[20:23]
	v_mfma_f32_16x16x32_bf16 v[8:11], v[230:233], v[222:225], v[8:11]
	v_mfma_f32_16x16x32_bf16 v[4:7], v[238:241], v[222:225], v[4:7]
	s_setprio 0
	s_add_i32 s48, 0, 0x18000
	v_add_u32_e32 v178, s48, v147
	s_barrier
	ds_read_b128 v[142:145], v178
	ds_read_b128 v[170:173], v178 offset:1024
	ds_read_b128 v[174:177], v178 offset:2048
	ds_read_b128 v[178:181], v178 offset:3072
	s_add_u32 s16, s20, 0x160000
	s_addc_u32 s17, s21, 0
	s_mov_b32 m0, s36
	v_lshl_add_u64 v[226:227], s[16:17], 0, v[132:133]
	ds_read_b128 v[182:185], v163 offset:32768
	ds_read_b128 v[186:189], v163 offset:33792
	ds_read_b128 v[190:193], v163 offset:34816
	ds_read_b128 v[194:197], v163 offset:35840
	ds_read_b128 v[198:201], v163 offset:36864
	ds_read_b128 v[214:217], v163 offset:37888
	ds_read_b128 v[218:221], v163 offset:38912
	ds_read_b128 v[222:225], v163 offset:39936
	global_load_lds_dwordx4 v[226:227], off
	v_lshl_add_u64 v[226:227], s[16:17], 0, v[134:135]
	s_mov_b32 m0, s37
	s_nop 0
	global_load_lds_dwordx4 v[226:227], off
	s_waitcnt lgkmcnt(8)
	s_barrier
; #define PG8_STAGE(bufoff, gbase, voff) do { _Pragma("unroll") for (int _i = 0; _i < 2; ++_i) \
;         __builtin_amdgcn_global_load_lds((const unsigned*)((const char*)(gbase) + (voff)[_i]), (LAS unsigned*)(lds + (bufoff) + ldsw + _i * 8192), 16, 0, 0); } while (0)
; #define PG8_LDA(dst, b, h) do { _Pragma("unroll") for (int m = 0; m < 4; ++m) _Pragma("unroll") for (int k = 0; k < 2; ++k) dst[m][k] = *(const LAS bf16x8*)(lds + PG8_SA(b, h) + aoff + m * 2048 + k * 1024); } while (0)
; #define PG8_LDB(dst, b, h) do { _Pragma("unroll") for (int n = 0; n < 2; ++n) _Pragma("unroll") for (int k = 0; k < 2; ++k) dst[n][k] = *(const LAS bf16x8*)(lds + PG8_SB(b, h) + boff + n * 2048 + k * 1024); } while (0)
; #define PG8_MMA(ai, bj, At, Bt) do { __builtin_amdgcn_s_setprio(1); _Pragma("unroll") for (int m = 0; m < 4; ++m) _Pragma("unroll") for (int n = 0; n < 2; ++n) _Pragma("unroll") for (int k = 0; k < 2; ++k) \
;         acc[ai][bj][m][n] = __builtin_amdgcn_mfma_f32_16x16x32_bf16(Bt[n][k], At[m][k], acc[ai][bj][m][n], 0, 0, 0); __builtin_amdgcn_s_setprio(0); } while (0)
; #define PG8_WAIT_L(n) asm volatile("s_waitcnt lgkmcnt(" #n ")" ::: "memory")
; #define PG8_BAR __builtin_amdgcn_s_barrier()
; #define PG8_SCHED __builtin_amdgcn_sched_barrier(0)
; template <class Epi>
; __device__ __forceinline__ void gemm_phase(LAS unsigned char* lds, const Gemm g, const StaticOrder& S, const Epi& E) {
;     ...
;             PG8_WAIT_L(8); PG8_BAR; PG8_WAIT_L(0); PG8_MMA(0, 0, At, B0); PG8_BAR; PG8_SCHED;
;             PG8_LDB(B1, 1, 1); PG8_STAGE(PG8_SB(1, 0), b3, voffB);
;             PG8_BAR; PG8_WAIT_L(0); PG8_MMA(0, 1, At, B1); PG8_BAR;
;             PG8_LDA(At, 1, 1); PG8_STAGE(PG8_SA(1, 0), a3, voffA);
;             PG8_BAR; PG8_WAIT_L(0); PG8_MMA(1, 0, At, B0); PG8_BAR; PG8_SCHED;
	s_waitcnt lgkmcnt(0)
	s_setprio 1
	s_waitcnt lgkmcnt(0)
	v_mfma_f32_16x16x32_bf16 v[128:131], v[142:145], v[182:185], v[128:131]
	v_mfma_f32_16x16x32_bf16 v[124:127], v[174:177], v[182:185], v[124:127]
	v_mfma_f32_16x16x32_bf16 v[112:115], v[142:145], v[190:193], v[112:115]
	v_mfma_f32_16x16x32_bf16 v[108:111], v[174:177], v[190:193], v[108:111]
	v_mfma_f32_16x16x32_bf16 v[96:99], v[142:145], v[198:201], v[96:99]
	v_mfma_f32_16x16x32_bf16 v[92:95], v[174:177], v[198:201], v[92:95]
	v_mfma_f32_16x16x32_bf16 v[80:83], v[142:145], v[218:221], v[80:83]
	v_mfma_f32_16x16x32_bf16 v[76:79], v[174:177], v[218:221], v[76:79]
	v_mfma_f32_16x16x32_bf16 v[128:131], v[170:173], v[186:189], v[128:131]
	v_mfma_f32_16x16x32_bf16 v[124:127], v[178:181], v[186:189], v[124:127]
	v_mfma_f32_16x16x32_bf16 v[112:115], v[170:173], v[194:197], v[112:115]
	v_mfma_f32_16x16x32_bf16 v[108:111], v[178:181], v[194:197], v[108:111]
	v_mfma_f32_16x16x32_bf16 v[96:99], v[170:173], v[214:217], v[96:99]
	v_mfma_f32_16x16x32_bf16 v[92:95], v[178:181], v[214:217], v[92:95]
	v_mfma_f32_16x16x32_bf16 v[80:83], v[170:173], v[222:225], v[80:83]
	v_mfma_f32_16x16x32_bf16 v[76:79], v[178:181], v[222:225], v[76:79]
	s_setprio 0
	s_barrier
	s_add_i32 s20, 0, 0x1c000
	s_add_i32 s16, s48, s30
	v_add_u32_e32 v238, s20, v147
	v_lshl_add_u64 v[242:243], v[242:243], 0, s[34:35]
	s_mov_b32 m0, s16
	ds_read_b128 v[226:229], v238
	ds_read_b128 v[230:233], v238 offset:1024
	ds_read_b128 v[234:237], v238 offset:2048
	ds_read_b128 v[238:241], v238 offset:3072
	global_load_lds_dwordx4 v[242:243], off
	v_lshl_add_u64 v[242:243], v[244:245], 0, s[34:35]
	s_add_i32 m0, s16, 0x2000
	s_nop 0
	global_load_lds_dwordx4 v[242:243], off
	s_barrier
	s_waitcnt lgkmcnt(0)
	s_setprio 1
	s_waitcnt lgkmcnt(0)
	v_mfma_f32_16x16x32_bf16 v[120:123], v[226:229], v[182:185], v[120:123]
	v_mfma_f32_16x16x32_bf16 v[116:119], v[234:237], v[182:185], v[116:119]
	v_mfma_f32_16x16x32_bf16 v[104:107], v[226:229], v[190:193], v[104:107]
	v_mfma_f32_16x16x32_bf16 v[100:103], v[234:237], v[190:193], v[100:103]
	v_mfma_f32_16x16x32_bf16 v[88:91], v[226:229], v[198:201], v[88:91]
	v_mfma_f32_16x16x32_bf16 v[84:87], v[234:237], v[198:201], v[84:87]
	v_mfma_f32_16x16x32_bf16 v[72:75], v[226:229], v[218:221], v[72:75]
	v_mfma_f32_16x16x32_bf16 v[68:71], v[234:237], v[218:221], v[68:71]
	v_mfma_f32_16x16x32_bf16 v[120:123], v[230:233], v[186:189], v[120:123]
	v_mfma_f32_16x16x32_bf16 v[116:119], v[238:241], v[186:189], v[116:119]
	v_mfma_f32_16x16x32_bf16 v[104:107], v[230:233], v[194:197], v[104:107]
	v_mfma_f32_16x16x32_bf16 v[100:103], v[238:241], v[194:197], v[100:103]
	v_mfma_f32_16x16x32_bf16 v[88:91], v[230:233], v[214:217], v[88:91]
	v_mfma_f32_16x16x32_bf16 v[84:87], v[238:241], v[214:217], v[84:87]
	v_mfma_f32_16x16x32_bf16 v[72:75], v[230:233], v[222:225], v[72:75]
	v_mfma_f32_16x16x32_bf16 v[68:71], v[238:241], v[222:225], v[68:71]
	s_setprio 0
	s_mov_b32 m0, s38
	v_lshl_add_u64 v[242:243], v[246:247], 0, s[34:35]
	s_barrier
	ds_read_b128 v[182:185], v163 offset:49152
	ds_read_b128 v[186:189], v163 offset:50176
	ds_read_b128 v[190:193], v163 offset:51200
	ds_read_b128 v[194:197], v163 offset:52224
	ds_read_b128 v[198:201], v163 offset:53248
	ds_read_b128 v[214:217], v163 offset:54272
	ds_read_b128 v[218:221], v163 offset:55296
	ds_read_b128 v[222:225], v163 offset:56320
	global_load_lds_dwordx4 v[242:243], off
	v_lshl_add_u64 v[242:243], v[248:249], 0, s[34:35]
	s_mov_b32 m0, s39
	s_nop 0
	global_load_lds_dwordx4 v[242:243], off
	s_barrier
	s_waitcnt lgkmcnt(0)
	s_setprio 1
	s_waitcnt lgkmcnt(0)
	v_mfma_f32_16x16x32_bf16 v[64:67], v[142:145], v[182:185], v[64:67]
	v_mfma_f32_16x16x32_bf16 v[60:63], v[174:177], v[182:185], v[60:63]
	v_mfma_f32_16x16x32_bf16 v[48:51], v[142:145], v[190:193], v[48:51]
	v_mfma_f32_16x16x32_bf16 v[44:47], v[174:177], v[190:193], v[44:47]
	v_mfma_f32_16x16x32_bf16 v[32:35], v[142:145], v[198:201], v[32:35]
	v_mfma_f32_16x16x32_bf16 v[28:31], v[174:177], v[198:201], v[28:31]
	v_mfma_f32_16x16x32_bf16 v[16:19], v[142:145], v[218:221], v[16:19]
	v_mfma_f32_16x16x32_bf16 v[12:15], v[174:177], v[218:221], v[12:15]
	v_mfma_f32_16x16x32_bf16 v[64:67], v[170:173], v[186:189], v[64:67]
	v_mfma_f32_16x16x32_bf16 v[60:63], v[178:181], v[186:189], v[60:63]
	v_mfma_f32_16x16x32_bf16 v[48:51], v[170:173], v[194:197], v[48:51]
	v_mfma_f32_16x16x32_bf16 v[44:47], v[178:181], v[194:197], v[44:47]
	v_mfma_f32_16x16x32_bf16 v[32:35], v[170:173], v[214:217], v[32:35]
	v_mfma_f32_16x16x32_bf16 v[28:31], v[178:181], v[214:217], v[28:31]
	v_mfma_f32_16x16x32_bf16 v[16:19], v[170:173], v[222:225], v[16:19]
	v_mfma_f32_16x16x32_bf16 v[12:15], v[178:181], v[222:225], v[12:15]
	s_setprio 0
	s_barrier
; #define PG8_STAGE(bufoff, gbase, voff) do { _Pragma("unroll") for (int _i = 0; _i < 2; ++_i) \
;         __builtin_amdgcn_global_load_lds((const unsigned*)((const char*)(gbase) + (voff)[_i]), (LAS unsigned*)(lds + (bufoff) + ldsw + _i * 8192), 16, 0, 0); } while (0)
; #define PG8_MMA(ai, bj, At, Bt) do { __builtin_amdgcn_s_setprio(1); _Pragma("unroll") for (int m = 0; m < 4; ++m) _Pragma("unroll") for (int n = 0; n < 2; ++n) _Pragma("unroll") for (int k = 0; k < 2; ++k) \
;         acc[ai][bj][m][n] = __builtin_amdgcn_mfma_f32_16x16x32_bf16(Bt[n][k], At[m][k], acc[ai][bj][m][n], 0, 0, 0); __builtin_amdgcn_s_setprio(0); } while (0)
; #define PG8_WAIT_V(n) asm volatile("s_waitcnt vmcnt(" #n ")" ::: "memory")
; #define PG8_BAR __builtin_amdgcn_s_barrier()
; template <class Epi>
; __device__ __forceinline__ void gemm_phase(LAS unsigned char* lds, const Gemm g, const StaticOrder& S, const Epi& E) {
;     ...
;             PG8_STAGE(PG8_SB(1, 1), b3 + hstep, voffB);
;             PG8_WAIT_V(6); PG8_BAR; PG8_MMA(1, 1, At, B1); PG8_BAR;
;         }
;         { Unit eu = cur; asm volatile("" : "+s"(eu.pm), "+s"(eu.pn)); E(acc, eu, wr, wc, fr, fq); }
;         if (!has_next) break;
;     __device__ __forceinline__ void operator()(const AccT& acc, const pg8::Unit& u, int wr, int wc, int fr, int fq) const {
;     ...
;                 const int row = row0 + ai * 128 + m * 16;
;                 if (row < NOUTROWS) {
;                     float ss = 0.f;
; #pragma unroll
;                     for (int bj = 0; bj < 2; ++bj) {
;                         const f32x4 v0 = acc[ai][bj][m][0] + __builtin_nontemporal_load((const f32x4*)(H1 + (size_t)row * DM + col0 + bj * 128));
;                         const f32x4 v1 = acc[ai][bj][m][1] + __builtin_nontemporal_load((const f32x4*)(H1 + (size_t)row * DM + col0 + bj * 128 + 4));
;                         *(f32x4*)(out + (size_t)row * DM + col0 + bj * 128) = v0; *(f32x4*)(out + (size_t)row * DM + col0 + bj * 128 + 4) = v1;
;                         ss += v0[0] * v0[0] + v0[1] * v0[1] + v0[2] * v0[2] + v0[3] * v0[3] + v1[0] * v1[0] + v1[1] * v1[1] + v1[2] * v1[2] + v1[3] * v1[3];
;                     }
;                     ss += __shfl_xor(ss, 16); ss += __shfl_xor(ss, 32);
;                     if (fq == 0) atomicAdd(SS3 + row, ss);
	s_add_u32 s16, s18, 0x160080
	s_addc_u32 s17, s19, 0
	s_add_i32 s18, s20, s30
	v_lshl_add_u64 v[142:143], s[16:17], 0, v[148:149]
	s_mov_b32 m0, s18
	s_nop 0
	global_load_lds_dwordx4 v[142:143], off
	v_lshl_add_u64 v[142:143], s[16:17], 0, v[136:137]
	s_add_i32 m0, s18, 0x2000
	s_nop 0
	global_load_lds_dwordx4 v[142:143], off
	s_waitcnt vmcnt(6)
	s_barrier
	s_setprio 1
	v_mfma_f32_16x16x32_bf16 v[56:59], v[226:229], v[182:185], v[56:59]
	v_mfma_f32_16x16x32_bf16 v[52:55], v[234:237], v[182:185], v[52:55]
	v_mfma_f32_16x16x32_bf16 v[40:43], v[226:229], v[190:193], v[40:43]
	v_mfma_f32_16x16x32_bf16 v[36:39], v[234:237], v[190:193], v[36:39]
	v_mfma_f32_16x16x32_bf16 v[24:27], v[226:229], v[198:201], v[24:27]
	v_mfma_f32_16x16x32_bf16 v[20:23], v[234:237], v[198:201], v[20:23]
	v_mfma_f32_16x16x32_bf16 v[8:11], v[226:229], v[218:221], v[8:11]
	v_mfma_f32_16x16x32_bf16 v[4:7], v[234:237], v[218:221], v[4:7]
	v_mfma_f32_16x16x32_bf16 v[56:59], v[230:233], v[186:189], v[56:59]
	v_mfma_f32_16x16x32_bf16 v[52:55], v[238:241], v[186:189], v[52:55]
	v_mfma_f32_16x16x32_bf16 v[40:43], v[230:233], v[194:197], v[40:43]
	v_mfma_f32_16x16x32_bf16 v[36:39], v[238:241], v[194:197], v[36:39]
	v_mfma_f32_16x16x32_bf16 v[24:27], v[230:233], v[214:217], v[24:27]
	v_mfma_f32_16x16x32_bf16 v[20:23], v[238:241], v[214:217], v[20:23]
	v_mfma_f32_16x16x32_bf16 v[8:11], v[230:233], v[222:225], v[8:11]
	v_mfma_f32_16x16x32_bf16 v[4:7], v[238:241], v[222:225], v[4:7]
	s_setprio 0
	s_add_i32 s47, s47, 2
	s_add_u32 s44, s44, 0x100
	s_addc_u32 s46, s46, 0
	s_cmpk_gt_u32 s47, 0x55
	s_mov_b64 s[16:17], s[6:7]
	s_barrier
	s_cbranch_scc0 .LBB0_23
	s_cmp_eq_u32 s40, 2
	s_cbranch_scc1 .Lp7_partial_epilogue
	s_movk_i32 s6, 0x2400
	v_lshl_or_b32 v142, s42, 8, v153
	v_lshl_add_u32 v144, s43, 8, v146
	v_ashrrev_i32_e32 v143, 31, v142
	v_cmp_gt_i32_e32 vcc, s6, v144
	v_lshlrev_b64 v[142:143], 2, v[142:143]
	s_and_saveexec_b64 s[6:7], vcc
	s_cbranch_execz .LBB0_27
	v_ashrrev_i32_e32 v145, 31, v144
	v_lshlrev_b64 v[178:179], 13, v[144:145]
	v_lshl_add_u64 v[170:171], s[2:3], 0, v[178:179]
	v_lshl_add_u64 v[180:181], v[170:171], 0, v[142:143]
	global_load_dwordx4 v[170:173], v[180:181], off nt
	global_load_dwordx4 v[174:177], v[180:181], off offset:16 nt
	v_readlane_b32 s16, v255, 31
	v_readlane_b32 s17, v255, 32
	s_waitcnt vmcnt(0)
	v_pk_add_f32 v[130:131], v[130:131], v[172:173]
	v_lshl_add_u64 v[178:179], s[16:17], 0, v[178:179]
	v_lshl_add_u64 v[178:179], v[178:179], 0, v[142:143]
	v_pk_add_f32 v[128:129], v[128:129], v[170:171]
	v_pk_add_f32 v[126:127], v[126:127], v[176:177]
	v_pk_add_f32 v[124:125], v[124:125], v[174:175]
	global_store_dwordx4 v[178:179], v[128:131], off
	global_store_dwordx4 v[178:179], v[124:127], off offset:16
	global_load_dwordx4 v[170:173], v[180:181], off offset:512 nt
	global_load_dwordx4 v[174:177], v[180:181], off offset:528 nt
	v_mul_f32_e32 v129, v129, v129
	v_fmac_f32_e32 v129, v128, v128
	v_fmac_f32_e32 v129, v130, v130
	v_fmac_f32_e32 v129, v131, v131
	v_fmac_f32_e32 v129, v124, v124
	v_fmac_f32_e32 v129, v125, v125
	v_and_b32_e32 v181, 64, v206
	v_fmac_f32_e32 v129, v126, v126
	v_xor_b32_e32 v180, 16, v206
	v_add_u32_e32 v181, 64, v181
	v_fmac_f32_e32 v129, v127, v127
	v_cmp_lt_i32_e32 vcc, v180, v181
	s_waitcnt vmcnt(0)
	v_pk_add_f32 v[120:121], v[120:121], v[170:171]
	v_pk_add_f32 v[124:125], v[116:117], v[174:175]
	v_mul_f32_e32 v116, v121, v121
	v_pk_add_f32 v[122:123], v[122:123], v[172:173]
	v_fmac_f32_e32 v116, v120, v120
	v_fmac_f32_e32 v116, v122, v122
	v_fmac_f32_e32 v116, v123, v123
	v_fmac_f32_e32 v116, v124, v124
	v_pk_add_f32 v[126:127], v[118:119], v[176:177]
	v_fmac_f32_e32 v116, v125, v125
	v_fmac_f32_e32 v116, v126, v126
	v_cndmask_b32_e32 v180, v206, v180, vcc
	v_fmac_f32_e32 v116, v127, v127
	v_lshlrev_b32_e32 v180, 2, v180
	v_add_f32_e32 v116, v129, v116
	ds_bpermute_b32 v117, v180, v116
	v_xor_b32_e32 v118, 32, v206
	v_cmp_lt_i32_e32 vcc, v118, v181
	global_store_dwordx4 v[178:179], v[120:123], off offset:512
	global_store_dwordx4 v[178:179], v[124:127], off offset:528
	v_cndmask_b32_e32 v118, v206, v118, vcc
	s_waitcnt lgkmcnt(0)
	v_add_f32_e32 v116, v116, v117
	v_lshlrev_b32_e32 v117, 2, v118
	ds_bpermute_b32 v117, v117, v116
	s_and_b64 exec, exec, s[8:9]
	s_cbranch_execz .LBB0_27
	v_lshl_add_u64 v[118:119], v[144:145], 2, s[12:13]
	s_waitcnt lgkmcnt(0)
	v_add_f32_e32 v116, v116, v117
	global_atomic_add_f32 v[118:119], v116, off

;     __device__ __forceinline__ void operator()(const AccT& acc, const pg8::Unit& u, int wr, int wc, int fr, int fq) const {
;         const int row0 = u.pm * 256 + wr * 64 + fr, col0 = u.pn * 256 + wc * 32 + 8 * fq;
; #pragma unroll
;         for (int ai = 0; ai < 2; ++ai)
; #pragma unroll
;             for (int m = 0; m < 4; ++m) {
;                 const int row = row0 + ai * 128 + m * 16;
;                 if (row < NOUTROWS) {
;                     float ss = 0.f;
; #pragma unroll
;                     for (int bj = 0; bj < 2; ++bj) {
;                         const f32x4 v0 = acc[ai][bj][m][0] + __builtin_nontemporal_load((const f32x4*)(H1 + (size_t)row * DM + col0 + bj * 128));
;                         const f32x4 v1 = acc[ai][bj][m][1] + __builtin_nontemporal_load((const f32x4*)(H1 + (size_t)row * DM + col0 + bj * 128 + 4));
;                         *(f32x4*)(out + (size_t)row * DM + col0 + bj * 128) = v0; *(f32x4*)(out + (size_t)row * DM + col0 + bj * 128 + 4) = v1;
.Lp7_partial_epilogue:
	s_mov_b32 s47, s50
	s_and_b32 s6, s22, 3
	s_lshl_b32 s6, s6, 23
	s_add_u32 s6, s6, 0xac00000
	s_add_u32 s6, s82, s6
	s_addc_u32 s7, s83, 0
	v_lshl_or_b32 v142, s42, 8, v153
	v_lshl_add_u32 v144, s43, 8, v146
	v_lshlrev_b32_e32 v142, 2, v142
	v_mov_b32_e32 v143, 0
	v_mov_b32_e32 v145, 0
	v_lshlrev_b64 v[170:171], 13, v[144:145]
	v_lshl_add_u64 v[170:171], s[6:7], 0, v[170:171]
	v_lshl_add_u64 v[170:171], v[170:171], 0, v[142:143]
	s_mov_b64 s[6:7], 0x20000
	s_mov_b64 s[16:17], 0xa0000
	global_store_dwordx4 v[170:171], v[128:131], off
	global_store_dwordx4 v[170:171], v[124:127], off offset:16
	global_store_dwordx4 v[170:171], v[120:123], off offset:512
	global_store_dwordx4 v[170:171], v[116:119], off offset:528
	v_lshl_add_u64 v[172:173], v[170:171], 0, s[6:7]
	global_store_dwordx4 v[172:173], v[112:115], off
	global_store_dwordx4 v[172:173], v[108:111], off offset:16
	global_store_dwordx4 v[172:173], v[104:107], off offset:512
	global_store_dwordx4 v[172:173], v[100:103], off offset:528
	v_lshl_add_u64 v[170:171], v[172:173], 0, s[6:7]
	global_store_dwordx4 v[170:171], v[96:99], off
	global_store_dwordx4 v[170:171], v[92:95], off offset:16
	global_store_dwordx4 v[170:171], v[88:91], off offset:512
	global_store_dwordx4 v[170:171], v[84:87], off offset:528
	v_lshl_add_u64 v[172:173], v[170:171], 0, s[6:7]
	global_store_dwordx4 v[172:173], v[80:83], off
	global_store_dwordx4 v[172:173], v[76:79], off offset:16
	global_store_dwordx4 v[172:173], v[72:75], off offset:512
	global_store_dwordx4 v[172:173], v[68:71], off offset:528
	v_lshl_add_u64 v[170:171], v[172:173], 0, s[16:17]
	global_store_dwordx4 v[170:171], v[64:67], off
	global_store_dwordx4 v[170:171], v[60:63], off offset:16
	global_store_dwordx4 v[170:171], v[56:59], off offset:512
	global_store_dwordx4 v[170:171], v[52:55], off offset:528
	v_lshl_add_u64 v[172:173], v[170:171], 0, s[6:7]
	global_store_dwordx4 v[172:173], v[48:51], off
	global_store_dwordx4 v[172:173], v[44:47], off offset:16
	global_store_dwordx4 v[172:173], v[40:43], off offset:512
	global_store_dwordx4 v[172:173], v[36:39], off offset:528
	v_lshl_add_u64 v[170:171], v[172:173], 0, s[6:7]
	global_store_dwordx4 v[170:171], v[32:35], off
	global_store_dwordx4 v[170:171], v[28:31], off offset:16
	global_store_dwordx4 v[170:171], v[24:27], off offset:512
	global_store_dwordx4 v[170:171], v[20:23], off offset:528
	v_lshl_add_u64 v[172:173], v[170:171], 0, s[6:7]
	global_store_dwordx4 v[172:173], v[16:19], off
	global_store_dwordx4 v[172:173], v[12:15], off offset:16
	global_store_dwordx4 v[172:173], v[8:11], off offset:512
	global_store_dwordx4 v[172:173], v[4:7], off offset:528
	s_mov_b64 s[6:7], 0
	s_branch .LBB0_15

; __device__ __forceinline__ int opaque_tid() { int t = threadIdx.x; asm volatile("" : "+v"(t)); return t; }
; __device__ __forceinline__ int opaque_bid() { int t = blockIdx.x; asm volatile("" : "+s"(t)); return t; }
; __device__ __forceinline__ void phase_final(const Params& p) {
;     const int tid = opaque_tid(), wid = tid >> 6, lane = tid & 63;
;     const float* SS3 = (const float*)(p.ws + WS_SS3); const float* nw = p.in[26];
;     const int step = gridDim.x * 8;
;     for (int row = opaque_bid() * 8 + wid; row < NOUTROWS; row += 2 * step) {
;         const int row2 = row + step; const bool has2 = row2 < NOUTROWS;
;         float* rp = p.out + (size_t)row * DM; float* rp2 = p.out + (size_t)(has2 ? row2 : row) * DM;
;         f32x4 v[8], v2[8];
; #pragma unroll
;         for (int it = 0; it < 8; ++it) v[it] = __builtin_nontemporal_load((const f32x4*)(rp + it * 256 + lane * 4));
; #pragma unroll
;         for (int it = 0; it < 8; ++it) v2[it] = __builtin_nontemporal_load((const f32x4*)(rp2 + it * 256 + lane * 4));
;         const float r = rsqrtf(SS3[row] * (1.f / 2048.f) + EPS), r2 = rsqrtf(SS3[has2 ? row2 : row] * (1.f / 2048.f) + EPS);
; #pragma unroll
;         for (int it = 0; it < 8; ++it) {
;             const int col = it * 256 + lane * 4;
;             const f32x4 w = *(const f32x4*)(nw + col);
;             __builtin_nontemporal_store(v[it] * r * w, (f32x4*)(rp + col));
;             if (has2) __builtin_nontemporal_store(v2[it] * r2 * w, (f32x4*)(rp2 + col));
.LBB0_860:
	s_nop 0
	v_readlane_b32 s0, v255, 33
	v_readlane_b32 s1, v255, 34
	s_and_b64 vcc, exec, s[0:1]
	s_cbranch_vccz .LBB0_881
	s_waitcnt vmcnt(0) lgkmcnt(0)
	v_readlane_b32 s0, v254, 0
	v_lshrrev_b32_e32 v4, 6, v151
	v_and_b32_e32 v5, 63, v151
	v_readlane_b32 s2, v255, 31
	v_readfirstlane_b32 s1, v4
	v_readlane_b32 s3, v255, 32
	v_readlane_b32 s4, v254, 37
	v_readlane_b32 s5, v254, 38
	s_lshl_b32 s0, s0, 3
	s_add_i32 s16, s0, s1
	v_lshlrev_b32_e32 v132, 4, v5
	v_add_u32_e32 v133, 0x1000, v132
	s_lshl_b32 s6, s16, 13
	s_add_u32 s20, s2, s6
	s_addc_u32 s21, s3, 0
	s_add_u32 s22, s20, 0x1000000
	s_addc_u32 s23, s21, 0
	s_add_u32 s24, s22, 0x1000000
	s_addc_u32 s25, s23, 0
	s_add_u32 s26, s24, 0x1000000
	s_addc_u32 s27, s25, 0
	s_lshl_b32 s6, s16, 2
	s_add_u32 s28, s82, 0x22b29400
	s_addc_u32 s29, s83, 0
	s_add_u32 s28, s28, s6
	s_addc_u32 s29, s29, 0
	v_mov_b32_e32 v142, 0x2000
	v_mov_b32_e32 v143, 0x4000
	v_mov_b32_e32 v144, 0x6000
	global_load_dword v134, v149, s[28:29]
	global_load_dword v136, v142, s[28:29]
	global_load_dword v138, v143, s[28:29]
	global_load_dword v140, v144, s[28:29]
	global_load_dwordx4 v[170:173], v132, s[4:5]
	global_load_dwordx4 v[174:177], v132, s[4:5] offset:1024
	global_load_dwordx4 v[178:181], v132, s[4:5] offset:2048
	global_load_dwordx4 v[182:185], v132, s[4:5] offset:3072
	global_load_dwordx4 v[186:189], v133, s[4:5]
	global_load_dwordx4 v[190:193], v133, s[4:5] offset:1024
	global_load_dwordx4 v[194:197], v133, s[4:5] offset:2048
	global_load_dwordx4 v[198:201], v133, s[4:5] offset:3072
	global_load_dwordx4 v[4:7], v132, s[20:21] nt
	global_load_dwordx4 v[8:11], v132, s[20:21] offset:1024 nt
	global_load_dwordx4 v[12:15], v132, s[20:21] offset:2048 nt
	global_load_dwordx4 v[16:19], v132, s[20:21] offset:3072 nt
	global_load_dwordx4 v[20:23], v133, s[20:21] nt
	global_load_dwordx4 v[24:27], v133, s[20:21] offset:1024 nt
	global_load_dwordx4 v[28:31], v133, s[20:21] offset:2048 nt
	global_load_dwordx4 v[32:35], v133, s[20:21] offset:3072 nt
	global_load_dwordx4 v[36:39], v132, s[22:23] nt
	global_load_dwordx4 v[40:43], v132, s[22:23] offset:1024 nt
	global_load_dwordx4 v[44:47], v132, s[22:23] offset:2048 nt
	global_load_dwordx4 v[48:51], v132, s[22:23] offset:3072 nt
	global_load_dwordx4 v[52:55], v133, s[22:23] nt
	global_load_dwordx4 v[56:59], v133, s[22:23] offset:1024 nt
	global_load_dwordx4 v[60:63], v133, s[22:23] offset:2048 nt
	global_load_dwordx4 v[64:67], v133, s[22:23] offset:3072 nt
	global_load_dwordx4 v[68:71], v132, s[24:25] nt
	global_load_dwordx4 v[72:75], v132, s[24:25] offset:1024 nt
	global_load_dwordx4 v[76:79], v132, s[24:25] offset:2048 nt
	global_load_dwordx4 v[80:83], v132, s[24:25] offset:3072 nt
	global_load_dwordx4 v[84:87], v133, s[24:25] nt
	global_load_dwordx4 v[88:91], v133, s[24:25] offset:1024 nt
	global_load_dwordx4 v[92:95], v133, s[24:25] offset:2048 nt
	global_load_dwordx4 v[96:99], v133, s[24:25] offset:3072 nt
	global_load_dwordx4 v[100:103], v132, s[26:27] nt
	global_load_dwordx4 v[104:107], v132, s[26:27] offset:1024 nt
	global_load_dwordx4 v[108:111], v132, s[26:27] offset:2048 nt
	global_load_dwordx4 v[112:115], v132, s[26:27] offset:3072 nt
	global_load_dwordx4 v[116:119], v133, s[26:27] nt
	global_load_dwordx4 v[120:123], v133, s[26:27] offset:1024 nt
	global_load_dwordx4 v[124:127], v133, s[26:27] offset:2048 nt
	global_load_dwordx4 v[128:131], v133, s[26:27] offset:3072 nt
	s_waitcnt vmcnt(40)
	v_fmamk_f32 v134, v134, 0x3a000000, v202
	v_fmamk_f32 v136, v136, 0x3a000000, v202
	v_fmamk_f32 v138, v138, 0x3a000000, v202
	v_fmamk_f32 v140, v140, 0x3a000000, v202
	v_rsq_f32_e32 v134, v134
	v_rsq_f32_e32 v136, v136
	v_rsq_f32_e32 v138, v138
	v_rsq_f32_e32 v140, v140
	s_waitcnt vmcnt(24)
	v_pk_mul_f32 v[4:5], v[4:5], v[134:135] op_sel_hi:[1,0]
	v_pk_mul_f32 v[6:7], v[6:7], v[134:135] op_sel_hi:[1,0]
	v_pk_mul_f32 v[4:5], v[4:5], v[170:171]
	v_pk_mul_f32 v[6:7], v[6:7], v[172:173]
	global_store_dwordx4 v132, v[4:7], s[20:21] nt
	v_pk_mul_f32 v[8:9], v[8:9], v[134:135] op_sel_hi:[1,0]
	v_pk_mul_f32 v[10:11], v[10:11], v[134:135] op_sel_hi:[1,0]
	v_pk_mul_f32 v[8:9], v[8:9], v[174:175]
	v_pk_mul_f32 v[10:11], v[10:11], v[176:177]
	global_store_dwordx4 v132, v[8:11], s[20:21] offset:1024 nt
	v_pk_mul_f32 v[12:13], v[12:13], v[134:135] op_sel_hi:[1,0]
	v_pk_mul_f32 v[14:15], v[14:15], v[134:135] op_sel_hi:[1,0]
	v_pk_mul_f32 v[12:13], v[12:13], v[178:179]
	v_pk_mul_f32 v[14:15], v[14:15], v[180:181]
	global_store_dwordx4 v132, v[12:15], s[20:21] offset:2048 nt
	v_pk_mul_f32 v[16:17], v[16:17], v[134:135] op_sel_hi:[1,0]
	v_pk_mul_f32 v[18:19], v[18:19], v[134:135] op_sel_hi:[1,0]
	v_pk_mul_f32 v[16:17], v[16:17], v[182:183]
	v_pk_mul_f32 v[18:19], v[18:19], v[184:185]
	global_store_dwordx4 v132, v[16:19], s[20:21] offset:3072 nt
	v_pk_mul_f32 v[20:21], v[20:21], v[134:135] op_sel_hi:[1,0]
	v_pk_mul_f32 v[22:23], v[22:23], v[134:135] op_sel_hi:[1,0]
	v_pk_mul_f32 v[20:21], v[20:21], v[186:187]
	v_pk_mul_f32 v[22:23], v[22:23], v[188:189]
	global_store_dwordx4 v133, v[20:23], s[20:21] nt
	v_pk_mul_f32 v[24:25], v[24:25], v[134:135] op_sel_hi:[1,0]
	v_pk_mul_f32 v[26:27], v[26:27], v[134:135] op_sel_hi:[1,0]
	v_pk_mul_f32 v[24:25], v[24:25], v[190:191]
	v_pk_mul_f32 v[26:27], v[26:27], v[192:193]
	global_store_dwordx4 v133, v[24:27], s[20:21] offset:1024 nt
	v_pk_mul_f32 v[28:29], v[28:29], v[134:135] op_sel_hi:[1,0]
	v_pk_mul_f32 v[30:31], v[30:31], v[134:135] op_sel_hi:[1,0]
	v_pk_mul_f32 v[28:29], v[28:29], v[194:195]
	v_pk_mul_f32 v[30:31], v[30:31], v[196:197]
	global_store_dwordx4 v133, v[28:31], s[20:21] offset:2048 nt
	v_pk_mul_f32 v[32:33], v[32:33], v[134:135] op_sel_hi:[1,0]
	v_pk_mul_f32 v[34:35], v[34:35], v[134:135] op_sel_hi:[1,0]
	v_pk_mul_f32 v[32:33], v[32:33], v[198:199]
	v_pk_mul_f32 v[34:35], v[34:35], v[200:201]
	global_store_dwordx4 v133, v[32:35], s[20:21] offset:3072 nt
	s_waitcnt vmcnt(24)
; __device__ __forceinline__ void phase_final(const Params& p) {
;     ...
; #pragma unroll
;         for (int it = 0; it < 8; ++it) {
;             const int col = it * 256 + lane * 4;
;             const f32x4 w = *(const f32x4*)(nw + col);
;             __builtin_nontemporal_store(v[it] * r * w, (f32x4*)(rp + col));
;             if (has2) __builtin_nontemporal_store(v2[it] * r2 * w, (f32x4*)(rp2 + col));
;         }
	v_pk_mul_f32 v[36:37], v[36:37], v[136:137] op_sel_hi:[1,0]
	v_pk_mul_f32 v[38:39], v[38:39], v[136:137] op_sel_hi:[1,0]
	v_pk_mul_f32 v[36:37], v[36:37], v[170:171]
	v_pk_mul_f32 v[38:39], v[38:39], v[172:173]
	global_store_dwordx4 v132, v[36:39], s[22:23] nt
	v_pk_mul_f32 v[40:41], v[40:41], v[136:137] op_sel_hi:[1,0]
	v_pk_mul_f32 v[42:43], v[42:43], v[136:137] op_sel_hi:[1,0]
	v_pk_mul_f32 v[40:41], v[40:41], v[174:175]
	v_pk_mul_f32 v[42:43], v[42:43], v[176:177]
	global_store_dwordx4 v132, v[40:43], s[22:23] offset:1024 nt
	v_pk_mul_f32 v[44:45], v[44:45], v[136:137] op_sel_hi:[1,0]
	v_pk_mul_f32 v[46:47], v[46:47], v[136:137] op_sel_hi:[1,0]
	v_pk_mul_f32 v[44:45], v[44:45], v[178:179]
	v_pk_mul_f32 v[46:47], v[46:47], v[180:181]
	global_store_dwordx4 v132, v[44:47], s[22:23] offset:2048 nt
	v_pk_mul_f32 v[48:49], v[48:49], v[136:137] op_sel_hi:[1,0]
	v_pk_mul_f32 v[50:51], v[50:51], v[136:137] op_sel_hi:[1,0]
	v_pk_mul_f32 v[48:49], v[48:49], v[182:183]
	v_pk_mul_f32 v[50:51], v[50:51], v[184:185]
	global_store_dwordx4 v132, v[48:51], s[22:23] offset:3072 nt
	v_pk_mul_f32 v[52:53], v[52:53], v[136:137] op_sel_hi:[1,0]
	v_pk_mul_f32 v[54:55], v[54:55], v[136:137] op_sel_hi:[1,0]
	v_pk_mul_f32 v[52:53], v[52:53], v[186:187]
	v_pk_mul_f32 v[54:55], v[54:55], v[188:189]
	global_store_dwordx4 v133, v[52:55], s[22:23] nt
	v_pk_mul_f32 v[56:57], v[56:57], v[136:137] op_sel_hi:[1,0]
	v_pk_mul_f32 v[58:59], v[58:59], v[136:137] op_sel_hi:[1,0]
	v_pk_mul_f32 v[56:57], v[56:57], v[190:191]
	v_pk_mul_f32 v[58:59], v[58:59], v[192:193]
	global_store_dwordx4 v133, v[56:59], s[22:23] offset:1024 nt
	v_pk_mul_f32 v[60:61], v[60:61], v[136:137] op_sel_hi:[1,0]
	v_pk_mul_f32 v[62:63], v[62:63], v[136:137] op_sel_hi:[1,0]
	v_pk_mul_f32 v[60:61], v[60:61], v[194:195]
	v_pk_mul_f32 v[62:63], v[62:63], v[196:197]
	global_store_dwordx4 v133, v[60:63], s[22:23] offset:2048 nt
	v_pk_mul_f32 v[64:65], v[64:65], v[136:137] op_sel_hi:[1,0]
	v_pk_mul_f32 v[66:67], v[66:67], v[136:137] op_sel_hi:[1,0]
	v_pk_mul_f32 v[64:65], v[64:65], v[198:199]
	v_pk_mul_f32 v[66:67], v[66:67], v[200:201]
	global_store_dwordx4 v133, v[64:67], s[22:23] offset:3072 nt
	s_waitcnt vmcnt(24)
	v_pk_mul_f32 v[68:69], v[68:69], v[138:139] op_sel_hi:[1,0]
	v_pk_mul_f32 v[70:71], v[70:71], v[138:139] op_sel_hi:[1,0]
	v_pk_mul_f32 v[68:69], v[68:69], v[170:171]
	v_pk_mul_f32 v[70:71], v[70:71], v[172:173]
	global_store_dwordx4 v132, v[68:71], s[24:25] nt
	v_pk_mul_f32 v[72:73], v[72:73], v[138:139] op_sel_hi:[1,0]
	v_pk_mul_f32 v[74:75], v[74:75], v[138:139] op_sel_hi:[1,0]
	v_pk_mul_f32 v[72:73], v[72:73], v[174:175]
	v_pk_mul_f32 v[74:75], v[74:75], v[176:177]
	global_store_dwordx4 v132, v[72:75], s[24:25] offset:1024 nt
	v_pk_mul_f32 v[76:77], v[76:77], v[138:139] op_sel_hi:[1,0]
	v_pk_mul_f32 v[78:79], v[78:79], v[138:139] op_sel_hi:[1,0]
	v_pk_mul_f32 v[76:77], v[76:77], v[178:179]
	v_pk_mul_f32 v[78:79], v[78:79], v[180:181]
	global_store_dwordx4 v132, v[76:79], s[24:25] offset:2048 nt
	v_pk_mul_f32 v[80:81], v[80:81], v[138:139] op_sel_hi:[1,0]
	v_pk_mul_f32 v[82:83], v[82:83], v[138:139] op_sel_hi:[1,0]
	v_pk_mul_f32 v[80:81], v[80:81], v[182:183]
	v_pk_mul_f32 v[82:83], v[82:83], v[184:185]
	global_store_dwordx4 v132, v[80:83], s[24:25] offset:3072 nt
	v_pk_mul_f32 v[84:85], v[84:85], v[138:139] op_sel_hi:[1,0]
	v_pk_mul_f32 v[86:87], v[86:87], v[138:139] op_sel_hi:[1,0]
	v_pk_mul_f32 v[84:85], v[84:85], v[186:187]
	v_pk_mul_f32 v[86:87], v[86:87], v[188:189]
	global_store_dwordx4 v133, v[84:87], s[24:25] nt
	v_pk_mul_f32 v[88:89], v[88:89], v[138:139] op_sel_hi:[1,0]
	v_pk_mul_f32 v[90:91], v[90:91], v[138:139] op_sel_hi:[1,0]
	v_pk_mul_f32 v[88:89], v[88:89], v[190:191]
	v_pk_mul_f32 v[90:91], v[90:91], v[192:193]
	global_store_dwordx4 v133, v[88:91], s[24:25] offset:1024 nt
	v_pk_mul_f32 v[92:93], v[92:93], v[138:139] op_sel_hi:[1,0]
	v_pk_mul_f32 v[94:95], v[94:95], v[138:139] op_sel_hi:[1,0]
	v_pk_mul_f32 v[92:93], v[92:93], v[194:195]
	v_pk_mul_f32 v[94:95], v[94:95], v[196:197]
	global_store_dwordx4 v133, v[92:95], s[24:25] offset:2048 nt
	v_pk_mul_f32 v[96:97], v[96:97], v[138:139] op_sel_hi:[1,0]
	v_pk_mul_f32 v[98:99], v[98:99], v[138:139] op_sel_hi:[1,0]
	v_pk_mul_f32 v[96:97], v[96:97], v[198:199]
	v_pk_mul_f32 v[98:99], v[98:99], v[200:201]
	global_store_dwordx4 v133, v[96:99], s[24:25] offset:3072 nt
	s_waitcnt vmcnt(24)
	v_pk_mul_f32 v[100:101], v[100:101], v[140:141] op_sel_hi:[1,0]
	v_pk_mul_f32 v[102:103], v[102:103], v[140:141] op_sel_hi:[1,0]
	v_pk_mul_f32 v[100:101], v[100:101], v[170:171]
	v_pk_mul_f32 v[102:103], v[102:103], v[172:173]
	global_store_dwordx4 v132, v[100:103], s[26:27] nt
	v_pk_mul_f32 v[104:105], v[104:105], v[140:141] op_sel_hi:[1,0]
	v_pk_mul_f32 v[106:107], v[106:107], v[140:141] op_sel_hi:[1,0]
	v_pk_mul_f32 v[104:105], v[104:105], v[174:175]
	v_pk_mul_f32 v[106:107], v[106:107], v[176:177]
	global_store_dwordx4 v132, v[104:107], s[26:27] offset:1024 nt
	v_pk_mul_f32 v[108:109], v[108:109], v[140:141] op_sel_hi:[1,0]
	v_pk_mul_f32 v[110:111], v[110:111], v[140:141] op_sel_hi:[1,0]
	v_pk_mul_f32 v[108:109], v[108:109], v[178:179]
	v_pk_mul_f32 v[110:111], v[110:111], v[180:181]
	global_store_dwordx4 v132, v[108:111], s[26:27] offset:2048 nt
	v_pk_mul_f32 v[112:113], v[112:113], v[140:141] op_sel_hi:[1,0]
	v_pk_mul_f32 v[114:115], v[114:115], v[140:141] op_sel_hi:[1,0]
	v_pk_mul_f32 v[112:113], v[112:113], v[182:183]
	v_pk_mul_f32 v[114:115], v[114:115], v[184:185]
	global_store_dwordx4 v132, v[112:115], s[26:27] offset:3072 nt
	v_pk_mul_f32 v[116:117], v[116:117], v[140:141] op_sel_hi:[1,0]
	v_pk_mul_f32 v[118:119], v[118:119], v[140:141] op_sel_hi:[1,0]
	v_pk_mul_f32 v[116:117], v[116:117], v[186:187]
	v_pk_mul_f32 v[118:119], v[118:119], v[188:189]
	global_store_dwordx4 v133, v[116:119], s[26:27] nt
	v_pk_mul_f32 v[120:121], v[120:121], v[140:141] op_sel_hi:[1,0]
	v_pk_mul_f32 v[122:123], v[122:123], v[140:141] op_sel_hi:[1,0]
	v_pk_mul_f32 v[120:121], v[120:121], v[190:191]
	v_pk_mul_f32 v[122:123], v[122:123], v[192:193]
	global_store_dwordx4 v133, v[120:123], s[26:27] offset:1024 nt
	v_pk_mul_f32 v[124:125], v[124:125], v[140:141] op_sel_hi:[1,0]
	v_pk_mul_f32 v[126:127], v[126:127], v[140:141] op_sel_hi:[1,0]
	v_pk_mul_f32 v[124:125], v[124:125], v[194:195]
	v_pk_mul_f32 v[126:127], v[126:127], v[196:197]
	global_store_dwordx4 v133, v[124:127], s[26:27] offset:2048 nt
	v_pk_mul_f32 v[128:129], v[128:129], v[140:141] op_sel_hi:[1,0]
	v_pk_mul_f32 v[130:131], v[130:131], v[140:141] op_sel_hi:[1,0]
	v_pk_mul_f32 v[128:129], v[128:129], v[198:199]
	v_pk_mul_f32 v[130:131], v[130:131], v[200:201]
	global_store_dwordx4 v133, v[128:131], s[26:27] offset:3072 nt
	s_cmpk_ge_u32 s16, 0x400
	s_cbranch_scc1 .Lp8_done
;     __device__ __forceinline__ void operator()(const AccT& acc, const pg8::Unit& u, int wr, int wc, int fr, int fq) const {
;     ...
;                         const f32x4 v0 = acc[ai][bj][m][0] + __builtin_nontemporal_load((const f32x4*)(H1 + (size_t)row * DM + col0 + bj * 128));
;                         const f32x4 v1 = acc[ai][bj][m][1] + __builtin_nontemporal_load((const f32x4*)(H1 + (size_t)row * DM + col0 + bj * 128 + 4));
;                         *(f32x4*)(out + (size_t)row * DM + col0 + bj * 128) = v0; *(f32x4*)(out + (size_t)row * DM + col0 + bj * 128 + 4) = v1;
;                         ss += v0[0] * v0[0] + v0[1] * v0[1] + v0[2] * v0[2] + v0[3] * v0[3] + v1[0] * v1[0] + v1[1] * v1[1] + v1[2] * v1[2] + v1[3] * v1[3];
; __device__ __forceinline__ void phase_final(const Params& p) {
;     ...
;         for (int it = 0; it < 8; ++it) v[it] = __builtin_nontemporal_load((const f32x4*)(rp + it * 256 + lane * 4));
; #pragma unroll
;         for (int it = 0; it < 8; ++it) v2[it] = __builtin_nontemporal_load((const f32x4*)(rp2 + it * 256 + lane * 4));
;         const float r = rsqrtf(SS3[row] * (1.f / 2048.f) + EPS), r2 = rsqrtf(SS3[has2 ? row2 : row] * (1.f / 2048.f) + EPS);
	s_lshl_b32 s6, s16, 13
	s_add_u32 s8, s82, 0x1f780000
	s_addc_u32 s9, s83, 0
	s_add_u32 s8, s8, s6
	s_addc_u32 s9, s9, 0
	s_add_u32 s10, s82, 0xec00000
	s_addc_u32 s11, s83, 0
	s_add_u32 s10, s10, s6
	s_addc_u32 s11, s11, 0
	s_add_u32 s12, s10, 0x800000
	s_addc_u32 s13, s11, 0
	s_add_u32 s14, s12, 0x800000
	s_addc_u32 s15, s13, 0
	s_add_u32 s18, s14, 0x800000
	s_addc_u32 s19, s15, 0
	s_add_u32 s20, s26, 0x1000000
	s_addc_u32 s21, s27, 0
	global_load_dwordx4 v[4:7], v132, s[8:9] nt
	global_load_dwordx4 v[8:11], v132, s[8:9] offset:1024 nt
	global_load_dwordx4 v[12:15], v132, s[8:9] offset:2048 nt
	global_load_dwordx4 v[16:19], v132, s[8:9] offset:3072 nt
	global_load_dwordx4 v[20:23], v133, s[8:9] nt
	global_load_dwordx4 v[24:27], v133, s[8:9] offset:1024 nt
	global_load_dwordx4 v[28:31], v133, s[8:9] offset:2048 nt
	global_load_dwordx4 v[32:35], v133, s[8:9] offset:3072 nt
	global_load_dwordx4 v[36:39], v132, s[10:11] nt
	global_load_dwordx4 v[40:43], v132, s[10:11] offset:1024 nt
	global_load_dwordx4 v[44:47], v132, s[10:11] offset:2048 nt
	global_load_dwordx4 v[48:51], v132, s[10:11] offset:3072 nt
	global_load_dwordx4 v[52:55], v133, s[10:11] nt
	global_load_dwordx4 v[56:59], v133, s[10:11] offset:1024 nt
	global_load_dwordx4 v[60:63], v133, s[10:11] offset:2048 nt
	global_load_dwordx4 v[64:67], v133, s[10:11] offset:3072 nt
	global_load_dwordx4 v[68:71], v132, s[12:13] nt
	global_load_dwordx4 v[72:75], v132, s[12:13] offset:1024 nt
	global_load_dwordx4 v[76:79], v132, s[12:13] offset:2048 nt
	global_load_dwordx4 v[80:83], v132, s[12:13] offset:3072 nt
	global_load_dwordx4 v[84:87], v133, s[12:13] nt
	global_load_dwordx4 v[88:91], v133, s[12:13] offset:1024 nt
	global_load_dwordx4 v[92:95], v133, s[12:13] offset:2048 nt
	global_load_dwordx4 v[96:99], v133, s[12:13] offset:3072 nt
	global_load_dwordx4 v[100:103], v132, s[14:15] nt
	global_load_dwordx4 v[104:107], v132, s[14:15] offset:1024 nt
	global_load_dwordx4 v[108:111], v132, s[14:15] offset:2048 nt
	global_load_dwordx4 v[112:115], v132, s[14:15] offset:3072 nt
	global_load_dwordx4 v[116:119], v133, s[14:15] nt
	global_load_dwordx4 v[120:123], v133, s[14:15] offset:1024 nt
	global_load_dwordx4 v[124:127], v133, s[14:15] offset:2048 nt
	global_load_dwordx4 v[128:131], v133, s[14:15] offset:3072 nt
	global_load_dwordx4 v[214:217], v132, s[18:19] nt
	global_load_dwordx4 v[218:221], v132, s[18:19] offset:1024 nt
	global_load_dwordx4 v[222:225], v132, s[18:19] offset:2048 nt
	global_load_dwordx4 v[226:229], v132, s[18:19] offset:3072 nt
	global_load_dwordx4 v[230:233], v133, s[18:19] nt
	global_load_dwordx4 v[234:237], v133, s[18:19] offset:1024 nt
	global_load_dwordx4 v[238:241], v133, s[18:19] offset:2048 nt
	global_load_dwordx4 v[242:245], v133, s[18:19] offset:3072 nt
	s_waitcnt vmcnt(24)
	v_pk_add_f32 v[4:5], v[4:5], v[36:37]
	v_pk_add_f32 v[6:7], v[6:7], v[38:39]
	v_pk_add_f32 v[8:9], v[8:9], v[40:41]
	v_pk_add_f32 v[10:11], v[10:11], v[42:43]
	v_pk_add_f32 v[12:13], v[12:13], v[44:45]
	v_pk_add_f32 v[14:15], v[14:15], v[46:47]
	v_pk_add_f32 v[16:17], v[16:17], v[48:49]
	v_pk_add_f32 v[18:19], v[18:19], v[50:51]
	v_pk_add_f32 v[20:21], v[20:21], v[52:53]
	v_pk_add_f32 v[22:23], v[22:23], v[54:55]
	v_pk_add_f32 v[24:25], v[24:25], v[56:57]
	v_pk_add_f32 v[26:27], v[26:27], v[58:59]
	v_pk_add_f32 v[28:29], v[28:29], v[60:61]
	v_pk_add_f32 v[30:31], v[30:31], v[62:63]
	v_pk_add_f32 v[32:33], v[32:33], v[64:65]
	v_pk_add_f32 v[34:35], v[34:35], v[66:67]
	s_waitcnt vmcnt(16)
	v_pk_add_f32 v[4:5], v[4:5], v[68:69]
	v_pk_add_f32 v[6:7], v[6:7], v[70:71]
	v_pk_add_f32 v[8:9], v[8:9], v[72:73]
	v_pk_add_f32 v[10:11], v[10:11], v[74:75]
	v_pk_add_f32 v[12:13], v[12:13], v[76:77]
	v_pk_add_f32 v[14:15], v[14:15], v[78:79]
	v_pk_add_f32 v[16:17], v[16:17], v[80:81]
	v_pk_add_f32 v[18:19], v[18:19], v[82:83]
	v_pk_add_f32 v[20:21], v[20:21], v[84:85]
	v_pk_add_f32 v[22:23], v[22:23], v[86:87]
	v_pk_add_f32 v[24:25], v[24:25], v[88:89]
	v_pk_add_f32 v[26:27], v[26:27], v[90:91]
	v_pk_add_f32 v[28:29], v[28:29], v[92:93]
	v_pk_add_f32 v[30:31], v[30:31], v[94:95]
	v_pk_add_f32 v[32:33], v[32:33], v[96:97]
	v_pk_add_f32 v[34:35], v[34:35], v[98:99]
	s_waitcnt vmcnt(8)
	v_pk_add_f32 v[4:5], v[4:5], v[100:101]
	v_pk_add_f32 v[6:7], v[6:7], v[102:103]
	v_pk_add_f32 v[8:9], v[8:9], v[104:105]
	v_pk_add_f32 v[10:11], v[10:11], v[106:107]
	v_pk_add_f32 v[12:13], v[12:13], v[108:109]
	v_pk_add_f32 v[14:15], v[14:15], v[110:111]
	v_pk_add_f32 v[16:17], v[16:17], v[112:113]
	v_pk_add_f32 v[18:19], v[18:19], v[114:115]
	v_pk_add_f32 v[20:21], v[20:21], v[116:117]
	v_pk_add_f32 v[22:23], v[22:23], v[118:119]
	v_pk_add_f32 v[24:25], v[24:25], v[120:121]
	v_pk_add_f32 v[26:27], v[26:27], v[122:123]
	v_pk_add_f32 v[28:29], v[28:29], v[124:125]
	v_pk_add_f32 v[30:31], v[30:31], v[126:127]
	v_pk_add_f32 v[32:33], v[32:33], v[128:129]
	v_pk_add_f32 v[34:35], v[34:35], v[130:131]
	s_waitcnt vmcnt(0)
;     __device__ __forceinline__ void operator()(const AccT& acc, const pg8::Unit& u, int wr, int wc, int fr, int fq) const {
;     ...
;                         ss += v0[0] * v0[0] + v0[1] * v0[1] + v0[2] * v0[2] + v0[3] * v0[3] + v1[0] * v1[0] + v1[1] * v1[1] + v1[2] * v1[2] + v1[3] * v1[3];
;                     }
;                     ss += __shfl_xor(ss, 16); ss += __shfl_xor(ss, 32);
; __device__ __forceinline__ void phase_final(const Params& p) {
;     ...
;         const float r = rsqrtf(SS3[row] * (1.f / 2048.f) + EPS), r2 = rsqrtf(SS3[has2 ? row2 : row] * (1.f / 2048.f) + EPS);
; #pragma unroll
;         for (int it = 0; it < 8; ++it) {
;             const int col = it * 256 + lane * 4;
;             const f32x4 w = *(const f32x4*)(nw + col);
;             __builtin_nontemporal_store(v[it] * r * w, (f32x4*)(rp + col));
;             if (has2) __builtin_nontemporal_store(v2[it] * r2 * w, (f32x4*)(rp2 + col));
;         }
	v_pk_add_f32 v[4:5], v[4:5], v[214:215]
	v_pk_add_f32 v[6:7], v[6:7], v[216:217]
	v_pk_add_f32 v[8:9], v[8:9], v[218:219]
	v_pk_add_f32 v[10:11], v[10:11], v[220:221]
	v_pk_add_f32 v[12:13], v[12:13], v[222:223]
	v_pk_add_f32 v[14:15], v[14:15], v[224:225]
	v_pk_add_f32 v[16:17], v[16:17], v[226:227]
	v_pk_add_f32 v[18:19], v[18:19], v[228:229]
	v_pk_add_f32 v[20:21], v[20:21], v[230:231]
	v_pk_add_f32 v[22:23], v[22:23], v[232:233]
	v_pk_add_f32 v[24:25], v[24:25], v[234:235]
	v_pk_add_f32 v[26:27], v[26:27], v[236:237]
	v_pk_add_f32 v[28:29], v[28:29], v[238:239]
	v_pk_add_f32 v[30:31], v[30:31], v[240:241]
	v_pk_add_f32 v[32:33], v[32:33], v[242:243]
	v_pk_add_f32 v[34:35], v[34:35], v[244:245]
	v_mul_f32_e32 v246, v4, v4
	v_mul_f32_e32 v247, v5, v5
	v_fmac_f32_e32 v246, v6, v6
	v_fmac_f32_e32 v247, v7, v7
	v_fmac_f32_e32 v246, v8, v8
	v_fmac_f32_e32 v247, v9, v9
	v_fmac_f32_e32 v246, v10, v10
	v_fmac_f32_e32 v247, v11, v11
	v_fmac_f32_e32 v246, v12, v12
	v_fmac_f32_e32 v247, v13, v13
	v_fmac_f32_e32 v246, v14, v14
	v_fmac_f32_e32 v247, v15, v15
	v_fmac_f32_e32 v246, v16, v16
	v_fmac_f32_e32 v247, v17, v17
	v_fmac_f32_e32 v246, v18, v18
	v_fmac_f32_e32 v247, v19, v19
	v_fmac_f32_e32 v246, v20, v20
	v_fmac_f32_e32 v247, v21, v21
	v_fmac_f32_e32 v246, v22, v22
	v_fmac_f32_e32 v247, v23, v23
	v_fmac_f32_e32 v246, v24, v24
	v_fmac_f32_e32 v247, v25, v25
	v_fmac_f32_e32 v246, v26, v26
	v_fmac_f32_e32 v247, v27, v27
	v_fmac_f32_e32 v246, v28, v28
	v_fmac_f32_e32 v247, v29, v29
	v_fmac_f32_e32 v246, v30, v30
	v_fmac_f32_e32 v247, v31, v31
	v_fmac_f32_e32 v246, v32, v32
	v_fmac_f32_e32 v247, v33, v33
	v_fmac_f32_e32 v246, v34, v34
	v_fmac_f32_e32 v247, v35, v35
	v_add_f32_e32 v246, v246, v247
	s_nop 1
	v_add_f32_dpp v246, v246, v246 quad_perm:[1,0,3,2] row_mask:0xf bank_mask:0xf
	s_nop 1
	v_add_f32_dpp v246, v246, v246 quad_perm:[2,3,0,1] row_mask:0xf bank_mask:0xf
	s_nop 1
	v_add_f32_dpp v246, v246, v246 row_half_mirror row_mask:0xf bank_mask:0xf
	s_nop 1
	v_add_f32_dpp v246, v246, v246 row_mirror row_mask:0xf bank_mask:0xf
	s_nop 1
	v_readlane_b32 s6, v246, 0
	v_readlane_b32 s7, v246, 16
	v_readlane_b32 s8, v246, 32
	v_readlane_b32 s9, v246, 48
	s_nop 1
	v_mov_b32_e32 v134, s6
	v_add_f32_e32 v134, s7, v134
	v_add_f32_e32 v134, s8, v134
	v_add_f32_e32 v134, s9, v134
	v_fmamk_f32 v134, v134, 0x3a000000, v202
	v_rsq_f32_e32 v134, v134
	s_nop 0
	v_pk_mul_f32 v[4:5], v[4:5], v[134:135] op_sel_hi:[1,0]
	v_pk_mul_f32 v[6:7], v[6:7], v[134:135] op_sel_hi:[1,0]
	v_pk_mul_f32 v[4:5], v[4:5], v[170:171]
	v_pk_mul_f32 v[6:7], v[6:7], v[172:173]
	global_store_dwordx4 v132, v[4:7], s[20:21] nt
	v_pk_mul_f32 v[8:9], v[8:9], v[134:135] op_sel_hi:[1,0]
	v_pk_mul_f32 v[10:11], v[10:11], v[134:135] op_sel_hi:[1,0]
	v_pk_mul_f32 v[8:9], v[8:9], v[174:175]
	v_pk_mul_f32 v[10:11], v[10:11], v[176:177]
	global_store_dwordx4 v132, v[8:11], s[20:21] offset:1024 nt
	v_pk_mul_f32 v[12:13], v[12:13], v[134:135] op_sel_hi:[1,0]
	v_pk_mul_f32 v[14:15], v[14:15], v[134:135] op_sel_hi:[1,0]
	v_pk_mul_f32 v[12:13], v[12:13], v[178:179]
	v_pk_mul_f32 v[14:15], v[14:15], v[180:181]
	global_store_dwordx4 v132, v[12:15], s[20:21] offset:2048 nt
	v_pk_mul_f32 v[16:17], v[16:17], v[134:135] op_sel_hi:[1,0]
	v_pk_mul_f32 v[18:19], v[18:19], v[134:135] op_sel_hi:[1,0]
	v_pk_mul_f32 v[16:17], v[16:17], v[182:183]
	v_pk_mul_f32 v[18:19], v[18:19], v[184:185]
	global_store_dwordx4 v132, v[16:19], s[20:21] offset:3072 nt
	v_pk_mul_f32 v[20:21], v[20:21], v[134:135] op_sel_hi:[1,0]
	v_pk_mul_f32 v[22:23], v[22:23], v[134:135] op_sel_hi:[1,0]
	v_pk_mul_f32 v[20:21], v[20:21], v[186:187]
	v_pk_mul_f32 v[22:23], v[22:23], v[188:189]
	global_store_dwordx4 v133, v[20:23], s[20:21] nt
	v_pk_mul_f32 v[24:25], v[24:25], v[134:135] op_sel_hi:[1,0]
	v_pk_mul_f32 v[26:27], v[26:27], v[134:135] op_sel_hi:[1,0]
	v_pk_mul_f32 v[24:25], v[24:25], v[190:191]
	v_pk_mul_f32 v[26:27], v[26:27], v[192:193]
	global_store_dwordx4 v133, v[24:27], s[20:21] offset:1024 nt
	v_pk_mul_f32 v[28:29], v[28:29], v[134:135] op_sel_hi:[1,0]
	v_pk_mul_f32 v[30:31], v[30:31], v[134:135] op_sel_hi:[1,0]
	v_pk_mul_f32 v[28:29], v[28:29], v[194:195]
	v_pk_mul_f32 v[30:31], v[30:31], v[196:197]
	global_store_dwordx4 v133, v[28:31], s[20:21] offset:2048 nt
	v_pk_mul_f32 v[32:33], v[32:33], v[134:135] op_sel_hi:[1,0]
	v_pk_mul_f32 v[34:35], v[34:35], v[134:135] op_sel_hi:[1,0]
	v_pk_mul_f32 v[32:33], v[32:33], v[198:199]
	v_pk_mul_f32 v[34:35], v[34:35], v[200:201]
	global_store_dwordx4 v133, v[32:35], s[20:21] offset:3072 nt
.Lp8_done:
	s_mov_b64 s[10:11], 0
.LBB0_881:
	s_andn2_b64 vcc, exec, s[10:11]
	s_cbranch_vccnz .LBB0_950
	s_waitcnt vmcnt(0)
	v_mov_b32_e32 v6, v151
	v_readlane_b32 s0, v254, 0
	s_nop 1
	v_lshl_add_u32 v4, s0, 9, v6
	s_movk_i32 s0, 0x4a00
	v_cmp_gt_i32_e32 vcc, s0, v4
	s_and_saveexec_b64 s[0:1], vcc
	s_cbranch_execz .LBB0_885
	s_add_u32 s2, s82, 0x22b20000
	s_addc_u32 s3, s83, 0
	s_mov_b64 s[4:5], 0
